# MLA loop: early LDS staging writes, out-of-line rescale, B loads hoisted, deferred adds, 3 PV MFMAs deferred across the barrier
# speedup vs baseline: 1.0175x; 1.0113x over previous
; #define LAS __attribute__((address_space(3)))
; __device__ __forceinline__ void mla_attn_phase(LAS unsigned char* lds, const bf16_t* q, const bf16_t* kv, const bf16_t* krope, const bf16_t* projb, bf16_t* y, int unit0, int G, int nu) {
;     ...
;     MLA_FETCH(unit);
;   for (;;) {
;     const int qb = unit & 15, h = (unit >> 4) & 15, s = unit >> 8;
;     const size_t row0 = (size_t)s * SEQ;
;     sb0 = *(const u32x4*)(src_kv + (size_t)192 * KVW); sb1 = *(const u32x4*)(src_kv + (size_t)224 * KVW); sb2 = *(const u32x4*)(src_r + (size_t)192 * 32);
; #pragma unroll
;     for (int t0 = 0; t0 < 3; ++t0) {
;         *(LAS u32x4*)(lds + t0 * MLA_BUF + dst_kv) = pre[3 * t0]; *(LAS u32x4*)(lds + t0 * MLA_BUF + dst_kv + dst_kv_step) = pre[3 * t0 + 1]; *(LAS u32x4*)(lds + ((tid < 256) ? t0 * MLA_BUF : 0) + dst_r) = pre[3 * t0 + 2];
;     }
;     __syncthreads();
;     f32x16 o0 = {0.f, 0.f, 0.f, 0.f, 0.f, 0.f, 0.f, 0.f, 0.f, 0.f, 0.f, 0.f, 0.f, 0.f, 0.f, 0.f}, o1 = o0, negm = o0;
;     const int voff = (4 * hi + ((lane & 15) >> 2)) * MLA_VS + (16 * ((lane >> 4) & 1) + 4 * (lane & 3)) * 2;
;     f32x16 c0, c1, n0, n1; u32x4 pa[4];
;     float m, lsum = 0.f;
;     MLA_QK(c0, c1, lds, negm);
;     { float tm; MLA_ROWMAX(c0, c1, tm); m = tm;
; #pragma unroll
;       for (int rr = 0; rr < 16; ++rr) { c0[rr] -= m; c1[rr] -= m; negm[rr] = -m; } }
;     int sl_c = 0, sl_n = MLA_BUF, sl_2 = 2 * MLA_BUF, sl_w = 3 * MLA_BUF, sl_4 = 4 * MLA_BUF;
.LBB0_201:
	s_mov_b32 s3, 0xc0000
	v_add_co_u32_e32 v0, vcc, s3, v206
	s_mov_b32 s3, 0xe0000
	s_nop 0
	v_addc_co_u32_e32 v1, vcc, 0, v207, vcc
	v_add_co_u32_e32 v2, vcc, s3, v206
	s_movk_i32 s3, 0x3000
	s_nop 0
	v_addc_co_u32_e32 v3, vcc, 0, v207, vcc
	global_load_dwordx4 v[152:155], v[0:1], off
	global_load_dwordx4 v[156:159], v[2:3], off
	v_add_co_u32_e32 v0, vcc, s3, v208
	v_add_u32_e32 v201, v185, v181
	s_nop 0
	v_addc_co_u32_e32 v1, vcc, 0, v209, vcc
	global_load_dwordx4 v[160:163], v[0:1], off
	s_waitcnt vmcnt(11)
	ds_write_b128 v185, v[32:35]
	s_waitcnt vmcnt(9)
	ds_write_b128 v201, v[40:43]
	ds_write_b128 v214, v[36:39]
	s_waitcnt vmcnt(8)
	ds_write_b128 v185, v[44:47] offset:25600
	s_waitcnt vmcnt(7)
	ds_write_b128 v201, v[48:51] offset:25600
	s_waitcnt vmcnt(4)
	ds_write_b128 v246, v[64:67]
	ds_write_b128 v185, v[52:55] offset:51200
	ds_write_b128 v201, v[56:59] offset:51200
	s_waitcnt vmcnt(3)
	ds_write_b128 v247, v[60:63]
	s_waitcnt lgkmcnt(0)
	s_barrier
	ds_read_b128 v[0:3], v215
	ds_read_b128 v[4:7], v215 offset:32
	s_waitcnt lgkmcnt(1)
	v_mfma_f32_32x32x16_bf16 v[32:47], v[0:3], v[148:151], 0
	ds_read_b128 v[0:3], v215 offset:6656
	ds_read_b128 v[8:11], v215 offset:6688
	s_mov_b32 s8, 0
	s_mov_b32 s9, s8
	s_mov_b32 s10, s8
	s_mov_b32 s11, s8
	s_mov_b32 s12, s8
	s_mov_b32 s13, s8
	s_waitcnt lgkmcnt(1)
	v_mfma_f32_32x32x16_bf16 v[16:31], v[0:3], v[148:151], 0
	s_mov_b32 s14, s8
	s_mov_b32 s15, s8
	s_mov_b32 s16, s8
	s_mov_b32 s17, s8
	s_mov_b32 s18, s8
	s_mov_b32 s19, s8
	s_mov_b32 s20, s8
	v_mfma_f32_32x32x16_bf16 v[32:47], v[4:7], v[144:147], v[32:47]
	ds_read_b128 v[0:3], v215 offset:64
	ds_read_b128 v[4:7], v215 offset:96
	s_mov_b32 s21, s8
	s_mov_b32 s22, s8
	s_mov_b32 s23, s8
	s_mov_b32 s3, 0x19000
	s_mov_b32 s6, 0x12c00
	s_mov_b32 s7, 0xc800
	s_waitcnt lgkmcnt(2)
	v_mfma_f32_32x32x16_bf16 v[16:31], v[8:11], v[144:147], v[16:31]
	v_mov_b32_e32 v205, 0
	s_waitcnt lgkmcnt(1)
	v_mfma_f32_32x32x16_bf16 v[32:47], v[0:3], v[140:143], v[32:47]
	ds_read_b128 v[0:3], v215 offset:6720
	ds_read_b128 v[8:11], v215 offset:6752
	s_waitcnt lgkmcnt(1)
	v_mfma_f32_32x32x16_bf16 v[16:31], v[0:3], v[140:143], v[16:31]
	v_mfma_f32_32x32x16_bf16 v[32:47], v[4:7], v[136:139], v[32:47]
	s_waitcnt lgkmcnt(0)
	v_mfma_f32_32x32x16_bf16 v[16:31], v[8:11], v[136:139], v[16:31]
	ds_read_b128 v[0:3], v215 offset:128
	ds_read_b128 v[4:7], v215 offset:6784
	ds_read_b128 v[8:11], v215 offset:160
	ds_read_b128 v[48:51], v215 offset:6816
	s_waitcnt lgkmcnt(3)
	v_mfma_f32_32x32x16_bf16 v[32:47], v[0:3], v[132:135], v[32:47]
	s_waitcnt lgkmcnt(2)
	v_mfma_f32_32x32x16_bf16 v[16:31], v[4:7], v[132:135], v[16:31]
	s_waitcnt lgkmcnt(1)
	v_mfma_f32_32x32x16_bf16 v[32:47], v[8:11], v[128:131], v[32:47]
	v_mov_b64_e32 v[0:1], s[8:9]
	v_mov_b64_e32 v[14:15], s[22:23]
	v_mov_b64_e32 v[2:3], s[10:11]
	v_mov_b64_e32 v[4:5], s[12:13]
	v_mov_b64_e32 v[6:7], s[14:15]
	v_mov_b64_e32 v[8:9], s[16:17]
	v_mov_b64_e32 v[10:11], s[18:19]
	s_waitcnt lgkmcnt(0)
	v_mfma_f32_32x32x16_bf16 v[16:31], v[48:51], v[128:131], v[16:31]
	s_nop 2
	v_max_f32_e32 v52, v33, v33
	v_max_f32_e32 v53, v32, v32
	v_max_f32_e32 v52, v53, v52
	v_mov_b64_e32 v[12:13], s[20:21]
	s_movk_i32 s12, 0x6400
	s_mov_b32 s9, -2
	s_nop 2
	v_max3_f32 v48, v34, v35, v17
	v_max3_f32 v49, v52, v16, v18
	v_max3_f32 v49, v49, v19, v36
	v_max3_f32 v48, v48, v38, v39
	v_max3_f32 v49, v49, v37, v20
	v_max3_f32 v48, v48, v22, v23
	v_max3_f32 v49, v49, v21, v40
	v_max3_f32 v48, v48, v42, v43
	v_max3_f32 v49, v49, v41, v24
	v_max3_f32 v48, v48, v26, v27
	v_max3_f32 v49, v49, v25, v44
	v_max3_f32 v48, v48, v46, v47
	v_max3_f32 v49, v49, v45, v28
	v_max3_f32 v48, v48, v30, v31
	v_max3_f32 v48, v49, v29, v48
	v_mov_b32_e32 v49, v48
	s_nop 1
	v_permlane32_swap_b32_e32 v48, v49
	v_max_f32_e32 v49, v49, v49
	v_max_f32_e32 v48, v48, v48
	v_max_f32_e32 v203, v48, v49
	v_xor_b32_e32 v48, 0x80000000, v203
	v_sub_f32_e32 v111, v31, v203
	v_sub_f32_e32 v110, v30, v203
	v_sub_f32_e32 v109, v29, v203
	v_sub_f32_e32 v108, v28, v203
	v_sub_f32_e32 v107, v27, v203
	v_sub_f32_e32 v106, v26, v203
	v_sub_f32_e32 v105, v25, v203
	v_sub_f32_e32 v104, v24, v203
	v_sub_f32_e32 v103, v23, v203
	v_sub_f32_e32 v102, v22, v203
	v_sub_f32_e32 v101, v21, v203
	v_sub_f32_e32 v100, v20, v203
	v_sub_f32_e32 v99, v19, v203
	v_sub_f32_e32 v98, v18, v203
	v_sub_f32_e32 v97, v17, v203
	v_sub_f32_e32 v96, v16, v203
	v_mov_b64_e32 v[30:31], v[14:15]
	v_sub_f32_e32 v95, v47, v203
	v_sub_f32_e32 v94, v46, v203
	v_sub_f32_e32 v93, v45, v203
	v_sub_f32_e32 v92, v44, v203
	v_sub_f32_e32 v91, v43, v203
	v_sub_f32_e32 v90, v42, v203
	v_sub_f32_e32 v89, v41, v203
	v_sub_f32_e32 v88, v40, v203
	v_sub_f32_e32 v87, v39, v203
	v_sub_f32_e32 v86, v38, v203
	v_sub_f32_e32 v85, v37, v203
	v_sub_f32_e32 v84, v36, v203
	v_sub_f32_e32 v83, v35, v203
	v_sub_f32_e32 v82, v34, v203
	v_sub_f32_e32 v81, v33, v203
	v_sub_f32_e32 v80, v32, v203
	v_mov_b64_e32 v[28:29], v[12:13]
	v_mov_b64_e32 v[26:27], v[10:11]
	v_mov_b64_e32 v[24:25], v[8:9]
	v_mov_b64_e32 v[22:23], v[6:7]
	v_mov_b64_e32 v[20:21], v[4:5]
	v_mov_b64_e32 v[18:19], v[2:3]
	v_mov_b64_e32 v[16:17], v[0:1]
	v_mov_b32_e32 v49, v48
	v_mov_b32_e32 v50, v48
	v_mov_b32_e32 v51, v48
	v_mov_b32_e32 v52, v48
	v_mov_b32_e32 v53, v48
	v_mov_b32_e32 v54, v48
	v_mov_b32_e32 v55, v48
	v_mov_b32_e32 v56, v48
	v_mov_b32_e32 v57, v48
	v_mov_b32_e32 v58, v48
	v_mov_b32_e32 v59, v48
	v_mov_b32_e32 v60, v48
	v_mov_b32_e32 v61, v48
	v_mov_b32_e32 v62, v48
	v_mov_b32_e32 v63, v48
	v_mov_b32_e32 v64, 0
	v_mov_b32_e32 v65, 0
	v_mov_b32_e32 v66, 0
	v_mov_b32_e32 v67, 0
	v_mov_b32_e32 v72, 0
	v_mov_b32_e32 v73, 0
	v_mov_b32_e32 v74, 0
	v_mov_b32_e32 v75, 0
	v_mov_b32_e32 v40, 0
	v_mov_b32_e32 v41, 0
	v_mov_b32_e32 v42, 0
	v_mov_b32_e32 v43, 0
	v_mov_b32_e32 v44, 0
	v_mov_b32_e32 v45, 0
	v_mov_b32_e32 v46, 0
	v_mov_b32_e32 v47, 0
	v_mov_b32_e32 v238, 0
	v_mov_b32_e32 v239, 0
	v_mov_b32_e32 v240, 0
	v_mov_b32_e32 v241, 0
; __device__ __forceinline__ void mla_attn_phase(LAS unsigned char* lds, const bf16_t* q, const bf16_t* kv, const bf16_t* krope, const bf16_t* projb, bf16_t* y, int unit0, int G, int nu) {
;     ...
; #pragma unroll 1
;     for (int t = 0; t < 62; t += 2) {
;         MLA_ITER(t, c0, c1, n0, n1, sa0, sa1, sa2, sb0, sb1, sb2, false);
;         MLA_ITER(t + 1, n0, n1, c0, c1, sb0, sb1, sb2, sa0, sa1, sa2, true);
;     }
.LBB0_202:
	s_add_i32 s9, s9, 2
	s_mov_b32 s11, s8
	s_mov_b32 s10, s12
	v_add_u32_e32 v242, s10, v215
	ds_read_b128 v[32:35], v242
	ds_read_b128 v[36:39], v242 offset:6656
	v_mfma_f32_32x32x16_bf16 v[16:31], v[64:67], v[40:43], v[16:31]
	ds_read_b128 v[40:43], v242 offset:32
	v_mfma_f32_32x32x16_bf16 v[0:15], v[72:75], v[44:47], v[0:15]
	ds_read_b128 v[44:47], v242 offset:6688
	v_mfma_f32_32x32x16_bf16 v[16:31], v[72:75], v[238:241], v[16:31]
	ds_read_b128 v[238:241], v242 offset:64
	v_add_u32_e32 v243, s11, v233
	s_min_u32 s8, s9, 59
	s_lshl_b32 s8, s8, 6
	s_addk_i32 s8, 0x100
	s_lshl_b32 s76, s8, 12
	v_lshl_add_u64 v[164:165], v[206:207], 0, s[76:77]
	v_add_co_u32_e32 v172, vcc, s83, v164
	s_lshl_b32 s76, s8, 6
	s_nop 0
	v_addc_co_u32_e32 v173, vcc, 0, v165, vcc
	global_load_dwordx4 v[164:167], v[164:165], off
	v_lshl_add_u64 v[168:169], v[208:209], 0, s[76:77]
	global_load_dwordx4 v[172:175], v[172:173], off
	global_load_dwordx4 v[168:171], v[168:169], off
	v_exp_f32_e32 v80, v80
	v_exp_f32_e32 v81, v81
	v_exp_f32_e32 v82, v82
	v_add_f32_e32 v205, v205, v80
	v_exp_f32_e32 v83, v83
	v_exp_f32_e32 v84, v84
	v_add_f32_e32 v205, v205, v82
	v_exp_f32_e32 v85, v85
	v_add_f32_e32 v252, v81, v83
	v_exp_f32_e32 v86, v86
	v_exp_f32_e32 v87, v87
	v_exp_f32_e32 v88, v88
	v_exp_f32_e32 v89, v89
	v_cvt_pk_bf16_f32 v80, v80, v81
	v_cvt_pk_bf16_f32 v81, v82, v83
	v_cvt_pk_bf16_f32 v82, v84, v85
	v_cvt_pk_bf16_f32 v83, v86, v87
	v_exp_f32_e32 v90, v90
	v_add_f32_e32 v205, v205, v88
	v_exp_f32_e32 v91, v91
	v_add_f32_e32 v252, v252, v89
	v_exp_f32_e32 v92, v92
	v_add_f32_e32 v205, v205, v90
	v_exp_f32_e32 v93, v93
	v_add_f32_e32 v252, v252, v91
	v_exp_f32_e32 v94, v94
	v_exp_f32_e32 v95, v95
	v_exp_f32_e32 v96, v96
	v_exp_f32_e32 v97, v97
	v_cvt_pk_bf16_f32 v88, v88, v89
	s_waitcnt lgkmcnt(3)
	v_mfma_f32_32x32x16_bf16 v[112:127], v[32:35], v[148:151], v[48:63]
	ds_read_b128 v[32:35], v242 offset:6720
	v_cvt_pk_bf16_f32 v89, v90, v91
	v_cvt_pk_bf16_f32 v90, v92, v93
	v_cvt_pk_bf16_f32 v91, v94, v95
	v_mfma_f32_32x32x16_bf16 v[64:79], v[36:39], v[148:151], v[48:63]
	ds_read_b128 v[36:39], v242 offset:96
	v_exp_f32_e32 v98, v98
	v_add_f32_e32 v205, v205, v96
	v_exp_f32_e32 v99, v99
	s_waitcnt lgkmcnt(3)
	v_mfma_f32_32x32x16_bf16 v[112:127], v[40:43], v[144:147], v[112:127]
	ds_read_b128 v[40:43], v242 offset:6752
	v_add_f32_e32 v252, v252, v97
	v_exp_f32_e32 v100, v100
	v_add_f32_e32 v205, v205, v98
	v_mfma_f32_32x32x16_bf16 v[64:79], v[44:47], v[144:147], v[64:79]
	ds_read_b128 v[44:47], v242 offset:128
	v_exp_f32_e32 v101, v101
	v_add_f32_e32 v252, v252, v99
	v_exp_f32_e32 v102, v102
	s_waitcnt lgkmcnt(3)
	v_mfma_f32_32x32x16_bf16 v[112:127], v[238:241], v[140:143], v[112:127]
	ds_read_b128 v[238:241], v242 offset:6784
	v_exp_f32_e32 v103, v103
	v_exp_f32_e32 v104, v104
	v_exp_f32_e32 v105, v105
	v_mfma_f32_32x32x16_bf16 v[64:79], v[32:35], v[140:143], v[64:79]
	ds_read_b128 v[32:35], v242 offset:160
	v_cvt_pk_bf16_f32 v96, v96, v97
	v_cvt_pk_bf16_f32 v97, v98, v99
	v_cvt_pk_bf16_f32 v98, v100, v101
	s_waitcnt lgkmcnt(3)
	v_mfma_f32_32x32x16_bf16 v[112:127], v[36:39], v[136:139], v[112:127]
	ds_read_b128 v[36:39], v242 offset:6816
	v_cvt_pk_bf16_f32 v99, v102, v103
	v_exp_f32_e32 v106, v106
	v_add_f32_e32 v205, v205, v104
	v_mfma_f32_32x32x16_bf16 v[64:79], v[40:43], v[136:139], v[64:79]
	ds_read_b64_tr_b16 v[40:41], v243 offset:13312
	ds_read_b64_tr_b16 v[42:43], v243 offset:14848
	v_exp_f32_e32 v107, v107
	v_add_f32_e32 v252, v252, v105
	v_exp_f32_e32 v108, v108
	s_waitcnt lgkmcnt(4)
	v_mfma_f32_32x32x16_bf16 v[112:127], v[44:47], v[132:135], v[112:127]
	ds_read_b64_tr_b16 v[44:45], v243 offset:13376
	ds_read_b64_tr_b16 v[46:47], v243 offset:14912
	v_add_f32_e32 v205, v205, v106
	v_exp_f32_e32 v109, v109
	v_add_f32_e32 v252, v252, v107
	v_mfma_f32_32x32x16_bf16 v[64:79], v[238:241], v[132:135], v[64:79]
	ds_read_b64_tr_b16 v[238:239], v243 offset:16384
	ds_read_b64_tr_b16 v[240:241], v243 offset:17920
	v_exp_f32_e32 v110, v110
	v_exp_f32_e32 v111, v111
	v_cvt_pk_bf16_f32 v104, v104, v105
	s_waitcnt lgkmcnt(6)
	v_mfma_f32_32x32x16_bf16 v[112:127], v[32:35], v[128:131], v[112:127]
	ds_read_b64_tr_b16 v[32:33], v243 offset:16448
	ds_read_b64_tr_b16 v[34:35], v243 offset:17984
	v_cvt_pk_bf16_f32 v105, v106, v107
	v_cvt_pk_bf16_f32 v106, v108, v109
	v_mfma_f32_32x32x16_bf16 v[64:79], v[36:39], v[128:131], v[64:79]
	ds_read_b64_tr_b16 v[36:37], v243 offset:19456
	ds_read_b64_tr_b16 v[38:39], v243 offset:20992
	v_cvt_pk_bf16_f32 v107, v110, v111
	s_waitcnt lgkmcnt(6)
	v_mfma_f32_32x32x16_bf16 v[0:15], v[80:83], v[40:43], v[0:15]
	ds_read_b64_tr_b16 v[40:41], v243 offset:19520
	ds_read_b64_tr_b16 v[42:43], v243 offset:21056
	v_add_f32_e32 v205, v205, v84
	v_add_f32_e32 v252, v252, v85
	v_add_f32_e32 v205, v205, v86
	v_add_f32_e32 v252, v252, v87
	v_mfma_f32_32x32x16_bf16 v[16:31], v[80:83], v[44:47], v[16:31]
	ds_read_b64_tr_b16 v[44:45], v243 offset:22528
	ds_read_b64_tr_b16 v[46:47], v243 offset:24064
	v_add_f32_e32 v205, v205, v92
	v_add_f32_e32 v252, v252, v93
	v_add_f32_e32 v205, v205, v94
	v_add_f32_e32 v252, v252, v95
	s_waitcnt lgkmcnt(6)
	v_mfma_f32_32x32x16_bf16 v[0:15], v[88:91], v[238:241], v[0:15]
	ds_read_b64_tr_b16 v[238:239], v243 offset:22592
	ds_read_b64_tr_b16 v[240:241], v243 offset:24128
	v_max_f32_e32 v191, v112, v113
	v_max_f32_e32 v178, v64, v65
	v_max3_f32 v191, v191, v114, v115
	v_add_f32_e32 v205, v205, v100
	v_add_f32_e32 v252, v252, v101
	v_mfma_f32_32x32x16_bf16 v[16:31], v[88:91], v[32:35], v[16:31]
	v_add_u32_e32 v242, s7, v215
	ds_read_b128 v[32:35], v242
	v_max3_f32 v178, v178, v66, v67
	v_max3_f32 v191, v191, v116, v117
	v_max3_f32 v178, v178, v68, v69
	v_add_f32_e32 v205, v205, v102
	v_add_f32_e32 v252, v252, v103
	s_waitcnt lgkmcnt(5)
	v_mfma_f32_32x32x16_bf16 v[0:15], v[96:99], v[36:39], v[0:15]
	ds_read_b128 v[36:39], v242 offset:6656
	v_max3_f32 v191, v191, v118, v119
	v_max3_f32 v178, v178, v70, v71
	v_max3_f32 v191, v191, v120, v121
	v_add_f32_e32 v205, v205, v108
	v_add_f32_e32 v252, v252, v109
	v_add_u32_e32 v177, s6, v185
	s_waitcnt vmcnt(5)
	ds_write_b128 v177, v[152:155]
	v_mfma_f32_32x32x16_bf16 v[16:31], v[96:99], v[40:43], v[16:31]
	ds_read_b128 v[40:43], v242 offset:32
	v_max3_f32 v178, v178, v72, v73
	v_max3_f32 v191, v191, v122, v123
	v_max3_f32 v178, v178, v74, v75
	v_add_f32_e32 v205, v205, v110
	v_add_f32_e32 v252, v252, v111
	v_add_u32_e32 v177, v177, v181
	s_waitcnt vmcnt(4)
	ds_write_b128 v177, v[156:159]
	s_waitcnt lgkmcnt(5)
	v_mfma_f32_32x32x16_bf16 v[0:15], v[104:107], v[44:47], v[0:15]
	ds_read_b128 v[44:47], v242 offset:6688
	v_max3_f32 v191, v191, v124, v125
	v_max3_f32 v178, v178, v76, v77
	v_max3_f32 v191, v191, v126, v127
	v_add_f32_e32 v205, v205, v252
	v_mov_b32_e32 v177, s6
	v_cndmask_b32_e64 v177, 0, v177, s[4:5]
	v_add_u32_e32 v177, v214, v177
	s_waitcnt vmcnt(3)
	ds_write_b128 v177, v[160:163]
	v_mfma_f32_32x32x16_bf16 v[16:31], v[104:107], v[238:241], v[16:31]
	ds_read_b128 v[238:241], v242 offset:64
	v_max3_f32 v178, v178, v78, v79
	v_max_f32_e32 v212, v191, v178
	v_mov_b32_e32 v253, v212
	s_min_u32 s8, s9, 58
	s_lshl_b32 s8, s8, 6
	s_addk_i32 s8, 0x140
	s_lshl_b32 s76, s8, 12
	v_lshl_add_u64 v[152:153], v[206:207], 0, s[76:77]
	v_add_co_u32_e32 v156, vcc, s83, v152
	s_lshl_b32 s76, s8, 6
	s_nop 0
	v_addc_co_u32_e32 v157, vcc, 0, v153, vcc
	global_load_dwordx4 v[152:155], v[152:153], off
	v_lshl_add_u64 v[160:161], v[208:209], 0, s[76:77]
	global_load_dwordx4 v[156:159], v[156:157], off
	global_load_dwordx4 v[160:163], v[160:161], off
	s_nop 1
	v_permlane32_swap_b32_e32 v212, v253
	v_max_f32_e32 v212, v212, v253
	v_cmp_lt_f32_e32 vcc, s58, v212
	s_cbranch_vccnz .Lmla_skip_a_ool
.Lmla_skip_a:
	v_add_u32_e32 v243, s10, v233
	s_waitcnt lgkmcnt(6)
	v_mfma_f32_32x32x16_bf16 v[80:95], v[32:35], v[148:151], v[48:63]
	ds_read_b128 v[32:35], v242 offset:6720
	v_exp_f32_e32 v112, v112
	v_exp_f32_e32 v113, v113
	v_exp_f32_e32 v114, v114
	v_add_f32_e32 v205, v205, v112
	v_exp_f32_e32 v115, v115
	v_mfma_f32_32x32x16_bf16 v[96:111], v[36:39], v[148:151], v[48:63]
	ds_read_b128 v[36:39], v242 offset:96
	v_exp_f32_e32 v116, v116
	v_add_f32_e32 v205, v205, v114
	v_exp_f32_e32 v117, v117
	v_add_f32_e32 v252, v113, v115
	v_exp_f32_e32 v118, v118
	s_waitcnt lgkmcnt(4)
	v_mfma_f32_32x32x16_bf16 v[80:95], v[40:43], v[144:147], v[80:95]
	ds_read_b128 v[40:43], v242 offset:6752
	v_exp_f32_e32 v119, v119
	v_exp_f32_e32 v120, v120
	v_exp_f32_e32 v121, v121
	v_cvt_pk_bf16_f32 v112, v112, v113
	v_cvt_pk_bf16_f32 v113, v114, v115
	v_mfma_f32_32x32x16_bf16 v[96:111], v[44:47], v[144:147], v[96:111]
	ds_read_b128 v[44:47], v242 offset:128
	v_cvt_pk_bf16_f32 v114, v116, v117
	v_cvt_pk_bf16_f32 v115, v118, v119
	v_exp_f32_e32 v122, v122
	v_add_f32_e32 v205, v205, v120
	v_exp_f32_e32 v123, v123
	s_waitcnt lgkmcnt(3)
	v_mfma_f32_32x32x16_bf16 v[80:95], v[238:241], v[140:143], v[80:95]
	ds_read_b128 v[238:241], v242 offset:6784
	v_add_f32_e32 v252, v252, v121
	v_exp_f32_e32 v124, v124
	v_add_f32_e32 v205, v205, v122
	v_exp_f32_e32 v125, v125
	v_add_f32_e32 v252, v252, v123
	v_mfma_f32_32x32x16_bf16 v[96:111], v[32:35], v[140:143], v[96:111]
	ds_read_b128 v[32:35], v242 offset:160
	v_exp_f32_e32 v126, v126
	v_exp_f32_e32 v127, v127
	v_exp_f32_e32 v64, v64
	v_exp_f32_e32 v65, v65
	v_cvt_pk_bf16_f32 v120, v120, v121
	s_waitcnt lgkmcnt(3)
	v_mfma_f32_32x32x16_bf16 v[80:95], v[36:39], v[136:139], v[80:95]
	ds_read_b128 v[36:39], v242 offset:6816
	v_cvt_pk_bf16_f32 v121, v122, v123
	v_cvt_pk_bf16_f32 v122, v124, v125
	v_cvt_pk_bf16_f32 v123, v126, v127
	v_exp_f32_e32 v66, v66
	v_add_f32_e32 v205, v205, v64
	v_mfma_f32_32x32x16_bf16 v[96:111], v[40:43], v[136:139], v[96:111]
	ds_read_b64_tr_b16 v[40:41], v243 offset:13312
	ds_read_b64_tr_b16 v[42:43], v243 offset:14848
	v_exp_f32_e32 v67, v67
	v_add_f32_e32 v252, v252, v65
	v_exp_f32_e32 v68, v68
	v_add_f32_e32 v205, v205, v66
	v_exp_f32_e32 v69, v69
	s_waitcnt lgkmcnt(4)
	v_mfma_f32_32x32x16_bf16 v[80:95], v[44:47], v[132:135], v[80:95]
	ds_read_b64_tr_b16 v[44:45], v243 offset:13376
	ds_read_b64_tr_b16 v[46:47], v243 offset:14912
	v_add_f32_e32 v252, v252, v67
	v_exp_f32_e32 v70, v70
	v_exp_f32_e32 v71, v71
	v_exp_f32_e32 v72, v72
	v_exp_f32_e32 v73, v73
	v_cvt_pk_bf16_f32 v64, v64, v65
	v_mfma_f32_32x32x16_bf16 v[96:111], v[238:241], v[132:135], v[96:111]
	ds_read_b64_tr_b16 v[238:239], v243 offset:16384
	ds_read_b64_tr_b16 v[240:241], v243 offset:17920
	v_cvt_pk_bf16_f32 v65, v66, v67
	v_cvt_pk_bf16_f32 v66, v68, v69
	v_cvt_pk_bf16_f32 v67, v70, v71
	v_exp_f32_e32 v74, v74
	v_add_f32_e32 v205, v205, v72
	v_exp_f32_e32 v75, v75
	s_waitcnt lgkmcnt(6)
	v_mfma_f32_32x32x16_bf16 v[80:95], v[32:35], v[128:131], v[80:95]
	ds_read_b64_tr_b16 v[32:33], v243 offset:16448
	ds_read_b64_tr_b16 v[34:35], v243 offset:17984
	v_add_f32_e32 v252, v252, v73
	v_exp_f32_e32 v76, v76
	v_add_f32_e32 v205, v205, v74
	v_exp_f32_e32 v77, v77
	v_add_f32_e32 v252, v252, v75
	v_exp_f32_e32 v78, v78
	v_mfma_f32_32x32x16_bf16 v[96:111], v[36:39], v[128:131], v[96:111]
	ds_read_b64_tr_b16 v[36:37], v243 offset:19456
	ds_read_b64_tr_b16 v[38:39], v243 offset:20992
	v_exp_f32_e32 v79, v79
	v_cvt_pk_bf16_f32 v72, v72, v73
	v_cvt_pk_bf16_f32 v73, v74, v75
	v_cvt_pk_bf16_f32 v74, v76, v77
	v_cvt_pk_bf16_f32 v75, v78, v79
	s_waitcnt lgkmcnt(6)
; __device__ __forceinline__ void mla_attn_phase(LAS unsigned char* lds, const bf16_t* q, const bf16_t* kv, const bf16_t* krope, const bf16_t* projb, bf16_t* y, int unit0, int G, int nu) {
;     ...
; #pragma unroll 1
;     for (int t = 0; t < 62; t += 2) {
;         MLA_ITER(t, c0, c1, n0, n1, sa0, sa1, sa2, sb0, sb1, sb2, false);
;         MLA_ITER(t + 1, n0, n1, c0, c1, sb0, sb1, sb2, sa0, sa1, sa2, true);
;     }
	v_mfma_f32_32x32x16_bf16 v[0:15], v[112:115], v[40:43], v[0:15]
	ds_read_b64_tr_b16 v[40:41], v243 offset:19520
	ds_read_b64_tr_b16 v[42:43], v243 offset:21056
	v_add_f32_e32 v205, v205, v116
	v_add_f32_e32 v252, v252, v117
	v_add_f32_e32 v205, v205, v118
	v_add_f32_e32 v252, v252, v119
	v_mfma_f32_32x32x16_bf16 v[16:31], v[112:115], v[44:47], v[16:31]
	ds_read_b64_tr_b16 v[44:45], v243 offset:22528
	ds_read_b64_tr_b16 v[46:47], v243 offset:24064
	v_add_f32_e32 v205, v205, v124
	v_add_f32_e32 v252, v252, v125
	v_add_f32_e32 v205, v205, v126
	v_add_f32_e32 v252, v252, v127
	s_waitcnt lgkmcnt(6)
	v_mfma_f32_32x32x16_bf16 v[0:15], v[120:123], v[238:241], v[0:15]
	ds_read_b64_tr_b16 v[238:239], v243 offset:22592
	ds_read_b64_tr_b16 v[240:241], v243 offset:24128
	v_max_f32_e32 v191, v80, v81
	v_max_f32_e32 v178, v96, v97
	v_max3_f32 v191, v191, v82, v83
	v_add_f32_e32 v205, v205, v68
	v_add_f32_e32 v252, v252, v69
	v_add_u32_e32 v177, s3, v185
	s_waitcnt vmcnt(5)
	ds_write_b128 v177, v[164:167]
	v_mfma_f32_32x32x16_bf16 v[16:31], v[120:123], v[32:35], v[16:31]
	v_max3_f32 v178, v178, v98, v99
	v_max3_f32 v191, v191, v84, v85
	v_max3_f32 v178, v178, v100, v101
	v_add_f32_e32 v205, v205, v70
	v_add_f32_e32 v252, v252, v71
	v_add_u32_e32 v177, v177, v181
	s_waitcnt vmcnt(4)
	ds_write_b128 v177, v[172:175]
	s_waitcnt lgkmcnt(8)
	v_mfma_f32_32x32x16_bf16 v[0:15], v[64:67], v[36:39], v[0:15]
	v_max3_f32 v191, v191, v86, v87
	v_max3_f32 v178, v178, v102, v103
	v_max3_f32 v191, v191, v88, v89
	v_add_f32_e32 v205, v205, v76
	v_add_f32_e32 v252, v252, v77
	v_mov_b32_e32 v177, s3
	v_cndmask_b32_e64 v177, 0, v177, s[4:5]
	v_add_u32_e32 v177, v214, v177
	s_waitcnt vmcnt(3)
	ds_write_b128 v177, v[168:171]
	v_max3_f32 v178, v178, v104, v105
	v_max3_f32 v191, v191, v90, v91
	v_max3_f32 v178, v178, v106, v107
	v_max3_f32 v191, v191, v92, v93
	v_max3_f32 v178, v178, v108, v109
	v_max3_f32 v191, v191, v94, v95
	v_max3_f32 v178, v178, v110, v111
	v_max_f32_e32 v212, v191, v178
	v_mov_b32_e32 v253, v212
	v_add_f32_e32 v205, v205, v78
	v_add_f32_e32 v252, v252, v79
	v_add_f32_e32 v205, v205, v252
	s_nop 1
	v_permlane32_swap_b32_e32 v212, v253
	v_max_f32_e32 v212, v212, v253
	v_cmp_lt_f32_e32 vcc, s58, v212
	s_cbranch_vccnz .Lmla_skip_b_ool
.Lmla_skip_b:
	s_cmp_lt_u32 s9, 60
	s_waitcnt lgkmcnt(0)
	s_barrier
	s_cbranch_scc0 .LBB0_209
	s_mov_b32 s8, s7
	s_mov_b32 s12, s6
	s_mov_b32 s7, s3
	s_mov_b32 s6, s11
	s_mov_b32 s3, s10
	s_branch .LBB0_202
.Lmla_skip_a_ool:
	s_nop 1
	v_cndmask_b32_e32 v100, 0, v212, vcc
	v_exp_f32_e64 v102, -v100
	v_add_f32_e32 v203, v203, v100
	v_xor_b32_e32 v101, 0x80000000, v203
	ds_bpermute_b32 v84, v217, v102
	ds_bpermute_b32 v85, v218, v102
	ds_bpermute_b32 v86, v219, v102
	ds_bpermute_b32 v87, v220, v102
	ds_bpermute_b32 v88, v221, v102
	ds_bpermute_b32 v89, v222, v102
	ds_bpermute_b32 v90, v223, v102
	ds_bpermute_b32 v91, v224, v102
	ds_bpermute_b32 v92, v225, v102
	ds_bpermute_b32 v93, v226, v102
	ds_bpermute_b32 v94, v227, v102
	ds_bpermute_b32 v95, v228, v102
	ds_bpermute_b32 v96, v229, v102
	ds_bpermute_b32 v97, v230, v102
	ds_bpermute_b32 v98, v231, v102
	ds_bpermute_b32 v99, v232, v102
	v_sub_f32_e32 v112, v112, v100
	v_sub_f32_e32 v113, v113, v100
	v_sub_f32_e32 v114, v114, v100
	v_sub_f32_e32 v115, v115, v100
	v_sub_f32_e32 v116, v116, v100
	v_sub_f32_e32 v117, v117, v100
	v_sub_f32_e32 v118, v118, v100
	v_sub_f32_e32 v119, v119, v100
	v_sub_f32_e32 v120, v120, v100
	v_sub_f32_e32 v121, v121, v100
	v_sub_f32_e32 v122, v122, v100
	v_sub_f32_e32 v123, v123, v100
	v_sub_f32_e32 v124, v124, v100
	v_sub_f32_e32 v125, v125, v100
	v_sub_f32_e32 v126, v126, v100
	v_sub_f32_e32 v127, v127, v100
	v_sub_f32_e32 v64, v64, v100
	v_sub_f32_e32 v65, v65, v100
	v_sub_f32_e32 v66, v66, v100
	v_sub_f32_e32 v67, v67, v100
	v_sub_f32_e32 v68, v68, v100
	v_sub_f32_e32 v69, v69, v100
	v_sub_f32_e32 v70, v70, v100
	v_sub_f32_e32 v71, v71, v100
	v_sub_f32_e32 v72, v72, v100
	v_sub_f32_e32 v73, v73, v100
	v_sub_f32_e32 v74, v74, v100
	v_sub_f32_e32 v75, v75, v100
	v_sub_f32_e32 v76, v76, v100
	v_sub_f32_e32 v77, v77, v100
	v_sub_f32_e32 v78, v78, v100
	v_sub_f32_e32 v79, v79, v100
	v_mul_f32_e32 v205, v205, v102
	v_mov_b32_e32 v48, v101
	v_mov_b32_e32 v49, v101
	v_mov_b32_e32 v50, v101
	v_mov_b32_e32 v51, v101
	v_mov_b32_e32 v52, v101
	v_mov_b32_e32 v53, v101
	v_mov_b32_e32 v54, v101
	v_mov_b32_e32 v55, v101
	v_mov_b32_e32 v56, v101
	v_mov_b32_e32 v57, v101
	v_mov_b32_e32 v58, v101
	v_mov_b32_e32 v59, v101
	v_mov_b32_e32 v60, v101
	v_mov_b32_e32 v61, v101
	v_mov_b32_e32 v62, v101
	v_mov_b32_e32 v63, v101
	s_waitcnt lgkmcnt(0)
	v_pk_mul_f32 v[0:1], v[0:1], v[84:85]
	v_pk_mul_f32 v[16:17], v[16:17], v[84:85]
	v_pk_mul_f32 v[2:3], v[2:3], v[86:87]
	v_pk_mul_f32 v[18:19], v[18:19], v[86:87]
	v_pk_mul_f32 v[4:5], v[4:5], v[88:89]
	v_pk_mul_f32 v[20:21], v[20:21], v[88:89]
	v_pk_mul_f32 v[6:7], v[6:7], v[90:91]
	v_pk_mul_f32 v[22:23], v[22:23], v[90:91]
	v_pk_mul_f32 v[8:9], v[8:9], v[92:93]
	v_pk_mul_f32 v[24:25], v[24:25], v[92:93]
	v_pk_mul_f32 v[10:11], v[10:11], v[94:95]
	v_pk_mul_f32 v[26:27], v[26:27], v[94:95]
	v_pk_mul_f32 v[12:13], v[12:13], v[96:97]
	v_pk_mul_f32 v[28:29], v[28:29], v[96:97]
	v_pk_mul_f32 v[14:15], v[14:15], v[98:99]
	v_pk_mul_f32 v[30:31], v[30:31], v[98:99]
	s_branch .Lmla_skip_a
; __device__ __forceinline__ void mla_attn_phase(LAS unsigned char* lds, const bf16_t* q, const bf16_t* kv, const bf16_t* krope, const bf16_t* projb, bf16_t* y, int unit0, int G, int nu) {
;     ...
; #pragma unroll 1
;     for (int t = 0; t < 62; t += 2) {
;         MLA_ITER(t, c0, c1, n0, n1, sa0, sa1, sa2, sb0, sb1, sb2, false);
;         MLA_ITER(t + 1, n0, n1, c0, c1, sb0, sb1, sb2, sa0, sa1, sa2, true);
;     }
;     MLA_ITER(62, c0, c1, n0, n1, sa0, sa1, sa2, sb0, sb1, sb2, false);
;     MLA_EXP(n0, n1);
;     MLA_PV(lds + sl_c + MLA_KB);
.Lmla_skip_b_ool:
	s_waitcnt lgkmcnt(0)
	v_mfma_f32_32x32x16_bf16 v[16:31], v[64:67], v[40:43], v[16:31]
	v_mfma_f32_32x32x16_bf16 v[0:15], v[72:75], v[44:47], v[0:15]
	v_mfma_f32_32x32x16_bf16 v[16:31], v[72:75], v[238:241], v[16:31]
	s_nop 1
	v_cndmask_b32_e32 v68, 0, v212, vcc
	v_exp_f32_e64 v70, -v68
	v_add_f32_e32 v203, v203, v68
	v_xor_b32_e32 v69, 0x80000000, v203
	ds_bpermute_b32 v116, v217, v70
	ds_bpermute_b32 v117, v218, v70
	ds_bpermute_b32 v118, v219, v70
	ds_bpermute_b32 v119, v220, v70
	ds_bpermute_b32 v120, v221, v70
	ds_bpermute_b32 v121, v222, v70
	ds_bpermute_b32 v122, v223, v70
	ds_bpermute_b32 v123, v224, v70
	ds_bpermute_b32 v124, v225, v70
	ds_bpermute_b32 v125, v226, v70
	ds_bpermute_b32 v126, v227, v70
	ds_bpermute_b32 v127, v228, v70
	ds_bpermute_b32 v64, v229, v70
	ds_bpermute_b32 v65, v230, v70
	ds_bpermute_b32 v66, v231, v70
	ds_bpermute_b32 v67, v232, v70
	v_sub_f32_e32 v80, v80, v68
	v_sub_f32_e32 v81, v81, v68
	v_sub_f32_e32 v82, v82, v68
	v_sub_f32_e32 v83, v83, v68
	v_sub_f32_e32 v84, v84, v68
	v_sub_f32_e32 v85, v85, v68
	v_sub_f32_e32 v86, v86, v68
	v_sub_f32_e32 v87, v87, v68
	v_sub_f32_e32 v88, v88, v68
	v_sub_f32_e32 v89, v89, v68
	v_sub_f32_e32 v90, v90, v68
	v_sub_f32_e32 v91, v91, v68
	v_sub_f32_e32 v92, v92, v68
	v_sub_f32_e32 v93, v93, v68
	v_sub_f32_e32 v94, v94, v68
	v_sub_f32_e32 v95, v95, v68
	v_sub_f32_e32 v96, v96, v68
	v_sub_f32_e32 v97, v97, v68
	v_sub_f32_e32 v98, v98, v68
	v_sub_f32_e32 v99, v99, v68
	v_sub_f32_e32 v100, v100, v68
	v_sub_f32_e32 v101, v101, v68
	v_sub_f32_e32 v102, v102, v68
	v_sub_f32_e32 v103, v103, v68
	v_sub_f32_e32 v104, v104, v68
	v_sub_f32_e32 v105, v105, v68
	v_sub_f32_e32 v106, v106, v68
	v_sub_f32_e32 v107, v107, v68
	v_sub_f32_e32 v108, v108, v68
	v_sub_f32_e32 v109, v109, v68
	v_sub_f32_e32 v110, v110, v68
	v_sub_f32_e32 v111, v111, v68
	v_mul_f32_e32 v205, v205, v70
	v_mov_b32_e32 v48, v69
	v_mov_b32_e32 v49, v69
	v_mov_b32_e32 v50, v69
	v_mov_b32_e32 v51, v69
	v_mov_b32_e32 v52, v69
	v_mov_b32_e32 v53, v69
	v_mov_b32_e32 v54, v69
	v_mov_b32_e32 v55, v69
	v_mov_b32_e32 v56, v69
	v_mov_b32_e32 v57, v69
	v_mov_b32_e32 v58, v69
	v_mov_b32_e32 v59, v69
	v_mov_b32_e32 v60, v69
	v_mov_b32_e32 v61, v69
	v_mov_b32_e32 v62, v69
	v_mov_b32_e32 v63, v69
	s_waitcnt lgkmcnt(0)
	v_pk_mul_f32 v[0:1], v[0:1], v[116:117]
	v_pk_mul_f32 v[16:17], v[16:17], v[116:117]
	v_pk_mul_f32 v[2:3], v[2:3], v[118:119]
	v_pk_mul_f32 v[18:19], v[18:19], v[118:119]
	v_pk_mul_f32 v[4:5], v[4:5], v[120:121]
	v_pk_mul_f32 v[20:21], v[20:21], v[120:121]
	v_pk_mul_f32 v[6:7], v[6:7], v[122:123]
	v_pk_mul_f32 v[22:23], v[22:23], v[122:123]
	v_pk_mul_f32 v[8:9], v[8:9], v[124:125]
	v_pk_mul_f32 v[24:25], v[24:25], v[124:125]
	v_pk_mul_f32 v[10:11], v[10:11], v[126:127]
	v_pk_mul_f32 v[26:27], v[26:27], v[126:127]
	v_pk_mul_f32 v[12:13], v[12:13], v[64:65]
	v_pk_mul_f32 v[28:29], v[28:29], v[64:65]
	v_pk_mul_f32 v[14:15], v[14:15], v[66:67]
	v_pk_mul_f32 v[30:31], v[30:31], v[66:67]
	v_mov_b32_e32 v64, 0
	v_mov_b32_e32 v65, 0
	v_mov_b32_e32 v66, 0
	v_mov_b32_e32 v67, 0
	v_mov_b32_e32 v72, 0
	v_mov_b32_e32 v73, 0
	v_mov_b32_e32 v74, 0
	v_mov_b32_e32 v75, 0
	s_branch .Lmla_skip_b
.LBB0_209:
	v_mfma_f32_32x32x16_bf16 v[16:31], v[64:67], v[40:43], v[16:31]
	v_mfma_f32_32x32x16_bf16 v[0:15], v[72:75], v[44:47], v[0:15]
	v_mfma_f32_32x32x16_bf16 v[16:31], v[72:75], v[238:241], v[16:31]
	v_mov_b64_e32 v[32:33], v[48:49]
	v_mov_b64_e32 v[34:35], v[50:51]
	v_mov_b64_e32 v[36:37], v[52:53]
	v_mov_b64_e32 v[38:39], v[54:55]
	v_mov_b64_e32 v[40:41], v[56:57]
	v_mov_b64_e32 v[42:43], v[58:59]
	v_mov_b64_e32 v[44:45], v[60:61]
	v_mov_b64_e32 v[46:47], v[62:63]
	ds_read_b128 v[64:67], v249
	ds_read_b128 v[68:71], v249 offset:32
	v_exp_f32_e32 v178, v81
	v_exp_f32_e32 v112, v97
	s_waitcnt lgkmcnt(1)
	v_mfma_f32_32x32x16_bf16 v[48:63], v[64:67], v[148:151], v[32:47]
	ds_read_b128 v[64:67], v248
	ds_read_b128 v[72:75], v248 offset:32
	s_waitcnt lgkmcnt(1)
	v_mfma_f32_32x32x16_bf16 v[32:47], v[64:67], v[148:151], v[32:47]
	s_waitcnt lgkmcnt(0)
	v_mfma_f32_32x32x16_bf16 v[32:47], v[72:75], v[144:147], v[32:47]
	v_exp_f32_e32 v73, v104
	v_exp_f32_e32 v104, v109
	v_exp_f32_e32 v74, v90
	v_exp_f32_e32 v75, v106
	v_exp_f32_e32 v90, v91
	v_exp_f32_e32 v72, v88
	v_exp_f32_e32 v88, v89
	v_mfma_f32_32x32x16_bf16 v[48:63], v[68:71], v[144:147], v[48:63]
	ds_read_b128 v[64:67], v248 offset:64
	ds_read_b128 v[68:71], v249 offset:64
	v_exp_f32_e32 v89, v110
	v_exp_f32_e32 v106, v111
	s_waitcnt lgkmcnt(1)
	v_mfma_f32_32x32x16_bf16 v[32:47], v[64:67], v[140:143], v[32:47]
	s_waitcnt lgkmcnt(0)
	v_mfma_f32_32x32x16_bf16 v[48:63], v[68:71], v[140:143], v[48:63]
	ds_read_b128 v[64:67], v248 offset:96
	ds_read_b128 v[68:71], v249 offset:96
	s_waitcnt lgkmcnt(1)
	v_mfma_f32_32x32x16_bf16 v[32:47], v[64:67], v[136:139], v[32:47]
	s_waitcnt lgkmcnt(0)
	v_mfma_f32_32x32x16_bf16 v[48:63], v[68:71], v[136:139], v[48:63]
	ds_read_b128 v[64:67], v248 offset:128
	ds_read_b128 v[68:71], v249 offset:128
	s_waitcnt lgkmcnt(1)
	v_mfma_f32_32x32x16_bf16 v[32:47], v[64:67], v[132:135], v[32:47]
	s_waitcnt lgkmcnt(0)
	v_mfma_f32_32x32x16_bf16 v[48:63], v[68:71], v[132:135], v[48:63]
	ds_read_b128 v[64:67], v248 offset:160
	ds_read_b128 v[68:71], v249 offset:160
	s_waitcnt lgkmcnt(1)
	v_mfma_f32_32x32x16_bf16 v[32:47], v[64:67], v[128:131], v[32:47]
	v_exp_f32_e32 v64, v80
	v_exp_f32_e32 v65, v96
	v_exp_f32_e32 v66, v82
	v_exp_f32_e32 v67, v98
	v_exp_f32_e32 v82, v83
	v_exp_f32_e32 v83, v92
	v_exp_f32_e32 v92, v93
	s_waitcnt lgkmcnt(0)
; __device__ __forceinline__ void mla_attn_phase(LAS unsigned char* lds, const bf16_t* q, const bf16_t* kv, const bf16_t* krope, const bf16_t* projb, bf16_t* y, int unit0, int G, int nu) {
;     ...
;     MLA_ITER(62, c0, c1, n0, n1, sa0, sa1, sa2, sb0, sb1, sb2, false);
;     MLA_EXP(n0, n1);
	v_mfma_f32_32x32x16_bf16 v[48:63], v[68:71], v[128:131], v[48:63]
	v_exp_f32_e32 v68, v84
	v_exp_f32_e32 v84, v85
	v_exp_f32_e32 v70, v86
	v_exp_f32_e32 v71, v102
	v_exp_f32_e32 v86, v87
	v_exp_f32_e32 v85, v108
	v_add_f32_e32 v113, v65, v64
	v_exp_f32_e32 v80, v99
	v_pk_add_f32 v[108:109], v[112:113], v[178:179]
	v_exp_f32_e32 v69, v100
	v_exp_f32_e32 v96, v101
	v_pk_add_f32 v[108:109], v[108:109], v[108:109] op_sel_hi:[0,1]
	v_add_f32_e32 v81, v67, v66
	v_add_f32_e32 v99, v71, v70
	v_exp_f32_e32 v100, v105
	v_add_f32_e32 v105, v85, v83
	v_cvt_pk_bf16_f32 v79, v70, v86
	v_cvt_pk_bf16_f32 v70, v83, v92
	v_mov_b32_e32 v83, v109
	v_cvt_pk_bf16_f32 v76, v64, v178
	v_cvt_pk_bf16_f32 v64, v65, v112
	v_cvt_pk_bf16_f32 v65, v67, v80
	v_pk_add_f32 v[80:81], v[80:81], v[82:83]
	v_exp_f32_e32 v98, v103
	v_exp_f32_e32 v87, v94
	v_exp_f32_e32 v94, v95
	v_pk_add_f32 v[80:81], v[80:81], v[80:81] op_sel_hi:[0,1]
	v_add_f32_e32 v97, v69, v68
	v_add_f32_e32 v103, v75, v74
	v_cvt_pk_bf16_f32 v77, v66, v82
	v_cvt_pk_bf16_f32 v66, v69, v96
	v_cvt_pk_bf16_f32 v69, v74, v90
	v_cvt_pk_bf16_f32 v74, v85, v104
	v_mov_b32_e32 v85, v81
	v_pk_add_f32 v[80:81], v[96:97], v[84:85]
	v_exp_f32_e32 v102, v107
	v_pk_add_f32 v[80:81], v[80:81], v[80:81] op_sel_hi:[0,1]
	v_add_f32_e32 v107, v89, v87
	v_cvt_pk_bf16_f32 v67, v71, v98
	v_cvt_pk_bf16_f32 v71, v87, v94
	v_mov_b32_e32 v87, v81
	v_pk_add_f32 v[80:81], v[98:99], v[86:87]
	v_add_f32_e32 v101, v73, v72
	v_pk_add_f32 v[80:81], v[80:81], v[80:81] op_sel_hi:[0,1]
	v_cvt_pk_bf16_f32 v78, v68, v84
	v_cvt_pk_bf16_f32 v68, v72, v88
	v_cvt_pk_bf16_f32 v72, v73, v100
	v_cvt_pk_bf16_f32 v73, v75, v102
	v_cvt_pk_bf16_f32 v75, v89, v106
	v_mov_b32_e32 v89, v81
	v_pk_add_f32 v[80:81], v[100:101], v[88:89]
	s_nop 0
	v_pk_add_f32 v[80:81], v[80:81], v[80:81] op_sel_hi:[0,1]
	v_mov_b32_e32 v91, v81
	v_pk_add_f32 v[80:81], v[102:103], v[90:91]
	s_nop 0
	v_pk_add_f32 v[80:81], v[80:81], v[80:81] op_sel_hi:[0,1]
	v_mov_b32_e32 v93, v81
	v_pk_add_f32 v[80:81], v[104:105], v[92:93]
	s_nop 0
	v_pk_add_f32 v[80:81], v[80:81], v[80:81] op_sel_hi:[0,1]
	v_mov_b32_e32 v95, v81
	v_pk_add_f32 v[80:81], v[106:107], v[94:95]
	s_nop 0
	v_add_f32_e32 v100, v80, v81
	ds_read_b64_tr_b16 v[80:81], v233 offset:64512
	ds_read_b64_tr_b16 v[82:83], v234 offset:1536
	ds_read_b64_tr_b16 v[84:85], v233 offset:64576
	ds_read_b64_tr_b16 v[86:87], v234 offset:1600
	s_waitcnt lgkmcnt(0)
	v_mfma_f32_32x32x16_bf16 v[16:31], v[76:79], v[84:87], v[16:31]
	ds_read_b64_tr_b16 v[84:85], v234 offset:3072
	ds_read_b64_tr_b16 v[86:87], v234 offset:4608
	ds_read_b64_tr_b16 v[88:89], v234 offset:3136
	ds_read_b64_tr_b16 v[90:91], v234 offset:4672
	v_mfma_f32_32x32x16_bf16 v[0:15], v[76:79], v[80:83], v[0:15]
	s_waitcnt lgkmcnt(0)
	v_mfma_f32_32x32x16_bf16 v[16:31], v[68:71], v[88:91], v[16:31]
	ds_read_b64_tr_b16 v[88:89], v234 offset:6144
	ds_read_b64_tr_b16 v[90:91], v234 offset:7680
	ds_read_b64_tr_b16 v[92:93], v234 offset:6208
	ds_read_b64_tr_b16 v[94:95], v234 offset:7744
	v_mfma_f32_32x32x16_bf16 v[0:15], v[68:71], v[84:87], v[0:15]
	s_waitcnt lgkmcnt(0)
	v_mfma_f32_32x32x16_bf16 v[16:31], v[64:67], v[92:95], v[16:31]
	ds_read_b64_tr_b16 v[92:93], v234 offset:9216
	ds_read_b64_tr_b16 v[94:95], v234 offset:10752
	ds_read_b64_tr_b16 v[96:97], v234 offset:9280
	ds_read_b64_tr_b16 v[98:99], v234 offset:10816
	v_mfma_f32_32x32x16_bf16 v[0:15], v[64:67], v[88:91], v[0:15]
	v_add_f32_e32 v64, v205, v100
	s_waitcnt lgkmcnt(0)
	v_mfma_f32_32x32x16_bf16 v[16:31], v[72:75], v[96:99], v[16:31]
	v_max_f32_e32 v96, v49, v49
	v_max_f32_e32 v97, v48, v48
	v_max_f32_e32 v96, v97, v96
	v_max3_f32 v97, v50, v51, v33
	v_max3_f32 v96, v96, v32, v34
	v_max3_f32 v96, v96, v35, v52
	v_max3_f32 v97, v97, v54, v55
	v_max3_f32 v96, v96, v53, v36
	v_max3_f32 v97, v97, v38, v39
	v_max3_f32 v96, v96, v37, v56
	v_max3_f32 v97, v97, v58, v59
	v_max3_f32 v96, v96, v57, v40
	v_max3_f32 v97, v97, v42, v43
	v_max3_f32 v96, v96, v41, v60
	v_max3_f32 v97, v97, v62, v63
	v_mfma_f32_32x32x16_bf16 v[0:15], v[72:75], v[92:95], v[0:15]
	v_max3_f32 v96, v96, v61, v44
	v_max3_f32 v97, v97, v46, v47
	v_max3_f32 v65, v96, v45, v97
	v_mov_b32_e32 v66, v65
	s_nop 1
	v_permlane32_swap_b32_e32 v65, v66
	v_max_f32_e32 v66, v66, v66
	v_max_f32_e32 v65, v65, v65
	v_max_f32_e32 v65, v65, v66
	v_cmp_lt_f32_e32 vcc, s58, v65
	s_cbranch_vccz .LBB0_200
	s_nop 0
	v_cndmask_b32_e32 v66, 0, v65, vcc
	v_exp_f32_e64 v65, -v66
	v_pk_add_f32 v[48:49], v[48:49], v[66:67] op_sel_hi:[1,0] neg_lo:[0,1] neg_hi:[0,1]
	v_pk_add_f32 v[32:33], v[32:33], v[66:67] op_sel_hi:[1,0] neg_lo:[0,1] neg_hi:[0,1]
	v_pk_add_f32 v[50:51], v[50:51], v[66:67] op_sel_hi:[1,0] neg_lo:[0,1] neg_hi:[0,1]
	ds_bpermute_b32 v68, v217, v65
	ds_bpermute_b32 v69, v218, v65
	ds_bpermute_b32 v70, v219, v65
	ds_bpermute_b32 v71, v220, v65
	ds_bpermute_b32 v72, v221, v65
	ds_bpermute_b32 v73, v222, v65
	ds_bpermute_b32 v74, v223, v65
	ds_bpermute_b32 v75, v224, v65
	ds_bpermute_b32 v76, v225, v65
	ds_bpermute_b32 v77, v226, v65
	ds_bpermute_b32 v78, v227, v65
	ds_bpermute_b32 v79, v228, v65
	ds_bpermute_b32 v80, v229, v65
	ds_bpermute_b32 v82, v231, v65
	ds_bpermute_b32 v83, v232, v65
	ds_bpermute_b32 v81, v230, v65
	v_pk_add_f32 v[34:35], v[34:35], v[66:67] op_sel_hi:[1,0] neg_lo:[0,1] neg_hi:[0,1]
	v_pk_add_f32 v[52:53], v[52:53], v[66:67] op_sel_hi:[1,0] neg_lo:[0,1] neg_hi:[0,1]
	v_pk_add_f32 v[36:37], v[36:37], v[66:67] op_sel_hi:[1,0] neg_lo:[0,1] neg_hi:[0,1]
	v_pk_add_f32 v[54:55], v[54:55], v[66:67] op_sel_hi:[1,0] neg_lo:[0,1] neg_hi:[0,1]
	v_pk_add_f32 v[38:39], v[38:39], v[66:67] op_sel_hi:[1,0] neg_lo:[0,1] neg_hi:[0,1]
	v_pk_add_f32 v[56:57], v[56:57], v[66:67] op_sel_hi:[1,0] neg_lo:[0,1] neg_hi:[0,1]
	v_pk_add_f32 v[40:41], v[40:41], v[66:67] op_sel_hi:[1,0] neg_lo:[0,1] neg_hi:[0,1]
	v_pk_add_f32 v[58:59], v[58:59], v[66:67] op_sel_hi:[1,0] neg_lo:[0,1] neg_hi:[0,1]
	v_pk_add_f32 v[42:43], v[42:43], v[66:67] op_sel_hi:[1,0] neg_lo:[0,1] neg_hi:[0,1]
	v_pk_add_f32 v[60:61], v[60:61], v[66:67] op_sel_hi:[1,0] neg_lo:[0,1] neg_hi:[0,1]
	v_pk_add_f32 v[44:45], v[44:45], v[66:67] op_sel_hi:[1,0] neg_lo:[0,1] neg_hi:[0,1]
	s_waitcnt lgkmcnt(1)
	v_pk_mul_f32 v[14:15], v[14:15], v[82:83]
	s_waitcnt lgkmcnt(0)
	v_pk_mul_f32 v[12:13], v[12:13], v[80:81]
	v_pk_mul_f32 v[10:11], v[10:11], v[78:79]
	v_pk_mul_f32 v[8:9], v[8:9], v[76:77]
	v_pk_mul_f32 v[6:7], v[6:7], v[74:75]
	v_pk_mul_f32 v[4:5], v[4:5], v[72:73]
	v_pk_mul_f32 v[2:3], v[2:3], v[70:71]
	v_pk_mul_f32 v[0:1], v[0:1], v[68:69]
	v_pk_mul_f32 v[30:31], v[30:31], v[82:83]
	v_pk_mul_f32 v[28:29], v[28:29], v[80:81]
	v_pk_mul_f32 v[26:27], v[26:27], v[78:79]
	v_pk_mul_f32 v[24:25], v[24:25], v[76:77]
	v_pk_mul_f32 v[22:23], v[22:23], v[74:75]
	v_pk_mul_f32 v[20:21], v[20:21], v[72:73]
	v_pk_mul_f32 v[18:19], v[18:19], v[70:71]
	v_pk_mul_f32 v[16:17], v[16:17], v[68:69]
	v_pk_add_f32 v[62:63], v[62:63], v[66:67] op_sel_hi:[1,0] neg_lo:[0,1] neg_hi:[0,1]
	v_pk_add_f32 v[46:47], v[46:47], v[66:67] op_sel_hi:[1,0] neg_lo:[0,1] neg_hi:[0,1]
	v_mul_f32_e32 v64, v64, v65
	s_branch .LBB0_200
